# P4 second-tile first K-iteration peeled with relaxed waits (epilogue atomics/stores stay in flight) on top of the prologue de-serialisation stack
# speedup vs baseline: 1.0029x; 1.0029x over previous
;     __device__ __forceinline__ const char* a(const Unit& u) const { return (const char*)A + (size_t)u.pm * 2 * hA(); }
;     __device__ __forceinline__ const char* b(const Unit& u) const { return (const char*)Bt + (size_t)u.pn * 2 * hB() + (size_t)(u.pm >> gshift) * goff; }
;     __device__ __forceinline__ const char* a(const Unit& u) const { return (const char*)A + (size_t)u.pm * 2 * hA(); }
;     __device__ __forceinline__ const char* b(const Unit& u) const { return (const char*)Bt + (size_t)((u.pn >> 4) * 4096 + (u.pn & 15) * 16) * 1024 * 2 + (size_t)(u.pm >> 1) * 512; }
;     __device__ __forceinline__ const char* a(const Unit&) const { return (const char*)A; }
;     __device__ __forceinline__ const char* b(const Unit& u) const { return (const char*)Bt + ((size_t)(((u.pm >> 4) * 1024 + u.pn * 256) * 16 + (u.pm & 15)) * 512) * 2; }
;     ...
; #pragma unroll
;         for (int a = 0; a < 2; ++a)
; #pragma unroll
;             for (int b = 0; b < 2; ++b)
; #pragma unroll
;                 for (int m = 0; m < 4; ++m)
; #pragma unroll
;                     for (int n = 0; n < 2; ++n) acc[a][b][m][n] = (f32x4){0.f, 0.f, 0.f, 0.f};
.LBB0_620:
	v_mov_b32_e32 v0, 0
	s_mov_b32 s55, -2
	s_mov_b64 s[6:7], s[16:17]
	s_mov_b64 s[20:21], s[18:19]
	v_mov_b32_e32 v1, v0
	v_mov_b32_e32 v2, v0
	v_mov_b32_e32 v3, v0
	v_mov_b32_e32 v4, v0
	v_mov_b32_e32 v5, v0
	v_mov_b32_e32 v6, v0
	v_mov_b32_e32 v7, v0
	v_mov_b32_e32 v16, v0
	v_mov_b32_e32 v17, v0
	v_mov_b32_e32 v18, v0
	v_mov_b32_e32 v19, v0
	v_mov_b32_e32 v20, v0
	v_mov_b32_e32 v21, v0
	v_mov_b32_e32 v22, v0
	v_mov_b32_e32 v23, v0
	v_mov_b32_e32 v32, v0
	v_mov_b32_e32 v33, v0
	v_mov_b32_e32 v34, v0
	v_mov_b32_e32 v35, v0
	v_mov_b32_e32 v36, v0
	v_mov_b32_e32 v37, v0
	v_mov_b32_e32 v38, v0
	v_mov_b32_e32 v39, v0
	v_mov_b32_e32 v48, v0
	v_mov_b32_e32 v49, v0
	v_mov_b32_e32 v50, v0
	v_mov_b32_e32 v51, v0
	v_mov_b32_e32 v52, v0
	v_mov_b32_e32 v53, v0
	v_mov_b32_e32 v54, v0
	v_mov_b32_e32 v55, v0
	v_mov_b32_e32 v8, v0
	v_mov_b32_e32 v9, v0
	v_mov_b32_e32 v10, v0
	v_mov_b32_e32 v11, v0
	v_mov_b32_e32 v12, v0
	v_mov_b32_e32 v13, v0
	v_mov_b32_e32 v14, v0
	v_mov_b32_e32 v15, v0
	v_mov_b32_e32 v24, v0
	v_mov_b32_e32 v25, v0
	v_mov_b32_e32 v26, v0
	v_mov_b32_e32 v27, v0
	v_mov_b32_e32 v28, v0
	v_mov_b32_e32 v29, v0
	v_mov_b32_e32 v30, v0
	v_mov_b32_e32 v31, v0
	v_mov_b32_e32 v40, v0
	v_mov_b32_e32 v41, v0
	v_mov_b32_e32 v42, v0
	v_mov_b32_e32 v43, v0
	v_mov_b32_e32 v44, v0
	v_mov_b32_e32 v45, v0
	v_mov_b32_e32 v46, v0
	v_mov_b32_e32 v47, v0
	v_mov_b32_e32 v56, v0
	v_mov_b32_e32 v57, v0
	v_mov_b32_e32 v58, v0
	v_mov_b32_e32 v59, v0
	v_mov_b32_e32 v60, v0
	v_mov_b32_e32 v61, v0
	v_mov_b32_e32 v62, v0
	v_mov_b32_e32 v63, v0
	v_mov_b32_e32 v64, v0
	v_mov_b32_e32 v65, v0
	v_mov_b32_e32 v66, v0
	v_mov_b32_e32 v67, v0
	v_mov_b32_e32 v68, v0
	v_mov_b32_e32 v69, v0
	v_mov_b32_e32 v70, v0
	v_mov_b32_e32 v71, v0
	v_mov_b32_e32 v80, v0
	v_mov_b32_e32 v81, v0
	v_mov_b32_e32 v82, v0
	v_mov_b32_e32 v83, v0
	v_mov_b32_e32 v84, v0
	v_mov_b32_e32 v85, v0
	v_mov_b32_e32 v86, v0
	v_mov_b32_e32 v87, v0
	v_mov_b32_e32 v96, v0
	v_mov_b32_e32 v97, v0
	v_mov_b32_e32 v98, v0
	v_mov_b32_e32 v99, v0
	v_mov_b32_e32 v100, v0
	v_mov_b32_e32 v101, v0
	v_mov_b32_e32 v102, v0
	v_mov_b32_e32 v103, v0
	v_mov_b32_e32 v112, v0
	v_mov_b32_e32 v113, v0
	v_mov_b32_e32 v114, v0
	v_mov_b32_e32 v115, v0
	v_mov_b32_e32 v116, v0
	v_mov_b32_e32 v117, v0
	v_mov_b32_e32 v118, v0
	v_mov_b32_e32 v119, v0
	v_mov_b32_e32 v72, v0
	v_mov_b32_e32 v73, v0
	v_mov_b32_e32 v74, v0
	v_mov_b32_e32 v75, v0
	v_mov_b32_e32 v76, v0
	v_mov_b32_e32 v77, v0
	v_mov_b32_e32 v78, v0
	v_mov_b32_e32 v79, v0
	v_mov_b32_e32 v88, v0
	v_mov_b32_e32 v89, v0
	v_mov_b32_e32 v90, v0
	v_mov_b32_e32 v91, v0
	v_mov_b32_e32 v92, v0
	v_mov_b32_e32 v93, v0
	v_mov_b32_e32 v94, v0
	v_mov_b32_e32 v95, v0
	v_mov_b32_e32 v104, v0
	v_mov_b32_e32 v105, v0
	v_mov_b32_e32 v106, v0
	v_mov_b32_e32 v107, v0
	v_mov_b32_e32 v108, v0
	v_mov_b32_e32 v109, v0
	v_mov_b32_e32 v110, v0
	v_mov_b32_e32 v111, v0
	v_mov_b32_e32 v120, v0
	v_mov_b32_e32 v121, v0
	v_mov_b32_e32 v122, v0
	v_mov_b32_e32 v123, v0
	v_mov_b32_e32 v124, v0
	v_mov_b32_e32 v125, v0
	v_mov_b32_e32 v126, v0
	v_mov_b32_e32 v127, v0
	s_cmp_lt_u32 s38, 2
	s_cbranch_scc1 .LBB0_621
	s_add_u32 s22, s20, 0x100
	s_addc_u32 s23, s21, 0
	s_add_u32 s24, s6, 0x100
	s_addc_u32 s25, s7, 0
	s_add_u32 s26, s20, 0x180
	s_addc_u32 s27, s21, 0
	s_add_u32 s28, s6, 0x180
	s_addc_u32 s29, s7, 0
	s_add_u32 s52, s20, 0x60080
	s_addc_u32 s53, s21, 0
	s_add_u32 s20, s20, 0x60100
	s_addc_u32 s21, s21, 0
	s_add_u32 s30, s6, 0x60100
	s_addc_u32 s31, s7, 0
	s_add_u32 s6, s6, 0x60180
	s_addc_u32 s7, s7, 0
	s_mov_b64 s[56:57], s[24:25]
	s_mov_b64 s[58:59], s[22:23]
	ds_read_b128 v[128:131], v187
	ds_read_b128 v[132:135], v187 offset:1024
	ds_read_b128 v[136:139], v187 offset:2048
	ds_read_b128 v[140:143], v187 offset:3072
	ds_read_b128 v[144:147], v189
	ds_read_b128 v[148:151], v189 offset:1024
	ds_read_b128 v[152:155], v189 offset:2048
	ds_read_b128 v[156:159], v189 offset:3072
	s_add_i32 s47, s34, 0xc000
	s_mov_b32 m0, s47
	s_add_i32 s49, s34, 0xe000
	ds_read_b128 v[160:163], v191
	ds_read_b128 v[164:167], v191 offset:1024
	ds_read_b128 v[168:171], v191 offset:2048
	ds_read_b128 v[172:175], v191 offset:3072
	ds_read_b128 v[176:179], v191 offset:4096
	ds_read_b128 v[180:183], v191 offset:5120
	ds_read_b128 v[196:199], v191 offset:6144
	ds_read_b128 v[200:203], v191 offset:7168
	global_load_lds_dwordx4 v184, s[52:53]
	s_mov_b32 m0, s49
	s_nop 0
	global_load_lds_dwordx4 v188, s[52:53]
	s_waitcnt vmcnt(48)
	s_waitcnt lgkmcnt(0)
	s_barrier
	s_setprio 1
	s_waitcnt lgkmcnt(0)
	v_mfma_f32_16x16x32_bf16 v[124:127], v[128:131], v[160:163], v[124:127]
	v_mfma_f32_16x16x32_bf16 v[120:123], v[136:139], v[160:163], v[120:123]
	v_mfma_f32_16x16x32_bf16 v[108:111], v[128:131], v[168:171], v[108:111]
	v_mfma_f32_16x16x32_bf16 v[104:107], v[136:139], v[168:171], v[104:107]
	v_mfma_f32_16x16x32_bf16 v[92:95], v[128:131], v[176:179], v[92:95]
	v_mfma_f32_16x16x32_bf16 v[88:91], v[136:139], v[176:179], v[88:91]
	v_mfma_f32_16x16x32_bf16 v[76:79], v[128:131], v[196:199], v[76:79]
	v_mfma_f32_16x16x32_bf16 v[72:75], v[136:139], v[196:199], v[72:75]
	v_mfma_f32_16x16x32_bf16 v[124:127], v[132:135], v[164:167], v[124:127]
	v_mfma_f32_16x16x32_bf16 v[120:123], v[140:143], v[164:167], v[120:123]
	v_mfma_f32_16x16x32_bf16 v[108:111], v[132:135], v[172:175], v[108:111]
	v_mfma_f32_16x16x32_bf16 v[104:107], v[140:143], v[172:175], v[104:107]
	v_mfma_f32_16x16x32_bf16 v[92:95], v[132:135], v[180:183], v[92:95]
	v_mfma_f32_16x16x32_bf16 v[88:91], v[140:143], v[180:183], v[88:91]
	v_mfma_f32_16x16x32_bf16 v[76:79], v[132:135], v[200:203], v[76:79]
	v_mfma_f32_16x16x32_bf16 v[72:75], v[140:143], v[200:203], v[72:75]
	s_setprio 0
	s_setprio 1
	v_mfma_f32_16x16x32_bf16 v[116:119], v[144:147], v[160:163], v[116:119]
	v_mfma_f32_16x16x32_bf16 v[112:115], v[152:155], v[160:163], v[112:115]
	v_mfma_f32_16x16x32_bf16 v[100:103], v[144:147], v[168:171], v[100:103]
	v_mfma_f32_16x16x32_bf16 v[96:99], v[152:155], v[168:171], v[96:99]
	v_mfma_f32_16x16x32_bf16 v[84:87], v[144:147], v[176:179], v[84:87]
	v_mfma_f32_16x16x32_bf16 v[80:83], v[152:155], v[176:179], v[80:83]
	v_mfma_f32_16x16x32_bf16 v[68:71], v[144:147], v[196:199], v[68:71]
	v_mfma_f32_16x16x32_bf16 v[64:67], v[152:155], v[196:199], v[64:67]
	v_mfma_f32_16x16x32_bf16 v[116:119], v[148:151], v[164:167], v[116:119]
	v_mfma_f32_16x16x32_bf16 v[112:115], v[156:159], v[164:167], v[112:115]
	v_mfma_f32_16x16x32_bf16 v[100:103], v[148:151], v[172:175], v[100:103]
	v_mfma_f32_16x16x32_bf16 v[96:99], v[156:159], v[172:175], v[96:99]
	v_mfma_f32_16x16x32_bf16 v[84:87], v[148:151], v[180:183], v[84:87]
	v_mfma_f32_16x16x32_bf16 v[80:83], v[156:159], v[180:183], v[80:83]
	v_mfma_f32_16x16x32_bf16 v[68:71], v[148:151], v[200:203], v[68:71]
	v_mfma_f32_16x16x32_bf16 v[64:67], v[156:159], v[200:203], v[64:67]
	s_setprio 0
	s_barrier
	s_add_i32 s51, s43, s33
	s_mov_b32 m0, s51
	s_add_i32 s52, s51, 0x2000
	ds_read_b128 v[160:163], v191 offset:16384
	ds_read_b128 v[164:167], v191 offset:17408
	ds_read_b128 v[168:171], v191 offset:18432
	ds_read_b128 v[172:175], v191 offset:19456
	ds_read_b128 v[176:179], v191 offset:20480
	ds_read_b128 v[180:183], v191 offset:21504
	ds_read_b128 v[196:199], v191 offset:22528
	ds_read_b128 v[200:203], v191 offset:23552
	global_load_lds_dwordx4 v186, s[56:57]
	s_mov_b32 m0, s52
	s_add_i32 s53, s44, s33
	global_load_lds_dwordx4 v190, s[56:57]
	s_mov_b32 m0, s53
	s_add_i32 s54, s53, 0x2000
	global_load_lds_dwordx4 v186, s[30:31]
	s_mov_b32 m0, s54
	s_nop 0
	global_load_lds_dwordx4 v190, s[30:31]
	s_mov_b32 m0, s34
	s_nop 0
	global_load_lds_dwordx4 v184, s[58:59]
	s_mov_b32 m0, s35
	s_nop 0
	global_load_lds_dwordx4 v188, s[58:59]
	s_waitcnt vmcnt(48)
	s_waitcnt lgkmcnt(0)
	s_barrier
	s_setprio 1
	s_waitcnt lgkmcnt(0)
	v_mfma_f32_16x16x32_bf16 v[60:63], v[128:131], v[160:163], v[60:63]
	v_mfma_f32_16x16x32_bf16 v[56:59], v[136:139], v[160:163], v[56:59]
	v_mfma_f32_16x16x32_bf16 v[44:47], v[128:131], v[168:171], v[44:47]
	v_mfma_f32_16x16x32_bf16 v[40:43], v[136:139], v[168:171], v[40:43]
	v_mfma_f32_16x16x32_bf16 v[28:31], v[128:131], v[176:179], v[28:31]
	v_mfma_f32_16x16x32_bf16 v[24:27], v[136:139], v[176:179], v[24:27]
	v_mfma_f32_16x16x32_bf16 v[12:15], v[128:131], v[196:199], v[12:15]
	v_mfma_f32_16x16x32_bf16 v[8:11], v[136:139], v[196:199], v[8:11]
	v_mfma_f32_16x16x32_bf16 v[60:63], v[132:135], v[164:167], v[60:63]
	v_mfma_f32_16x16x32_bf16 v[56:59], v[140:143], v[164:167], v[56:59]
	v_mfma_f32_16x16x32_bf16 v[44:47], v[132:135], v[172:175], v[44:47]
	v_mfma_f32_16x16x32_bf16 v[40:43], v[140:143], v[172:175], v[40:43]
	v_mfma_f32_16x16x32_bf16 v[28:31], v[132:135], v[180:183], v[28:31]
	v_mfma_f32_16x16x32_bf16 v[24:27], v[140:143], v[180:183], v[24:27]
	v_mfma_f32_16x16x32_bf16 v[12:15], v[132:135], v[200:203], v[12:15]
	v_mfma_f32_16x16x32_bf16 v[8:11], v[140:143], v[200:203], v[8:11]
	s_setprio 0
	s_setprio 1
	v_mfma_f32_16x16x32_bf16 v[52:55], v[144:147], v[160:163], v[52:55]
	v_mfma_f32_16x16x32_bf16 v[48:51], v[152:155], v[160:163], v[48:51]
	v_mfma_f32_16x16x32_bf16 v[36:39], v[144:147], v[168:171], v[36:39]
	v_mfma_f32_16x16x32_bf16 v[32:35], v[152:155], v[168:171], v[32:35]
	v_mfma_f32_16x16x32_bf16 v[20:23], v[144:147], v[176:179], v[20:23]
	v_mfma_f32_16x16x32_bf16 v[16:19], v[152:155], v[176:179], v[16:19]
	v_mfma_f32_16x16x32_bf16 v[4:7], v[144:147], v[196:199], v[4:7]
	v_mfma_f32_16x16x32_bf16 v[0:3], v[152:155], v[196:199], v[0:3]
	v_mfma_f32_16x16x32_bf16 v[52:55], v[148:151], v[164:167], v[52:55]
	v_mfma_f32_16x16x32_bf16 v[48:51], v[156:159], v[164:167], v[48:51]
	v_mfma_f32_16x16x32_bf16 v[36:39], v[148:151], v[172:175], v[36:39]
	v_mfma_f32_16x16x32_bf16 v[32:35], v[156:159], v[172:175], v[32:35]
	v_mfma_f32_16x16x32_bf16 v[20:23], v[148:151], v[180:183], v[20:23]
	v_mfma_f32_16x16x32_bf16 v[16:19], v[156:159], v[180:183], v[16:19]
	v_mfma_f32_16x16x32_bf16 v[4:7], v[148:151], v[200:203], v[4:7]
	v_mfma_f32_16x16x32_bf16 v[0:3], v[156:159], v[200:203], v[0:3]
	s_setprio 0
	s_barrier
	s_add_i32 s30, 0, 0x18000
	s_add_i32 s56, 0, 0x1c000
	v_add_u32_e32 v128, s30, v185
	v_add_u32_e32 v129, s56, v185
	ds_read_b128 v[130:133], v128
	ds_read_b128 v[134:137], v128 offset:1024
	ds_read_b128 v[138:141], v128 offset:2048
	ds_read_b128 v[142:145], v128 offset:3072
	ds_read_b128 v[146:149], v129
	ds_read_b128 v[150:153], v129 offset:1024
	ds_read_b128 v[154:157], v129 offset:2048
	ds_read_b128 v[158:161], v129 offset:3072
	s_mov_b32 m0, s36
	ds_read_b128 v[162:165], v191 offset:32768
	ds_read_b128 v[166:169], v191 offset:33792
	ds_read_b128 v[170:173], v191 offset:34816
	ds_read_b128 v[174:177], v191 offset:35840
	ds_read_b128 v[178:181], v191 offset:36864
	ds_read_b128 v[196:199], v191 offset:37888
	ds_read_b128 v[200:203], v191 offset:38912
	ds_read_b128 v[204:207], v191 offset:39936
	global_load_lds_dwordx4 v184, s[20:21]
	s_mov_b32 m0, s37
	s_nop 0
	global_load_lds_dwordx4 v188, s[20:21]
	s_waitcnt vmcnt(8)
	s_waitcnt lgkmcnt(0)
	s_barrier
; #define PG8_MMA(ai, bj, At, Bt) do { __builtin_amdgcn_s_setprio(1); _Pragma("unroll") for (int m = 0; m < 4; ++m) _Pragma("unroll") for (int n = 0; n < 2; ++n) _Pragma("unroll") for (int k = 0; k < 2; ++k) \
;         acc[ai][bj][m][n] = __builtin_amdgcn_mfma_f32_16x16x32_bf16(Bt[n][k], At[m][k], acc[ai][bj][m][n], 0, 0, 0); __builtin_amdgcn_s_setprio(0); } while (0)
; #define PG8_MMA8(ai, bj, At, Bt) do { __builtin_amdgcn_s_setprio(1); _Pragma("unroll") for (int m = 0; m < 4; ++m) _Pragma("unroll") for (int n = 0; n < 2; ++n) \
;         acc[ai][bj][m][n] = __builtin_amdgcn_mfma_scale_f32_16x16x128_f8f6f4(PG8_CAT(Bt[n][0], Bt[n][1]), PG8_CAT(At[m][0], At[m][1]), acc[ai][bj][m][n], 0, 0, 0, 0, 0, 0); __builtin_amdgcn_s_setprio(0); } while (0)
;     ...
;         { const int tmid = (TSW > 0 && TSW < nt) ? TSW : nt;
;           _Pragma("unroll 1") for (int t = 0; t < tmid; t += 2) { PG8_BODY(PG8_MMA) }
;           if constexpr (TSW > 0) { _Pragma("unroll 1") for (int t = tmid; t < nt; t += 2) { PG8_BODY(PG8_MMA8) } } }
	s_setprio 1
	s_waitcnt lgkmcnt(0)
	v_mfma_f32_16x16x32_bf16 v[124:127], v[130:133], v[162:165], v[124:127]
	v_mfma_f32_16x16x32_bf16 v[120:123], v[138:141], v[162:165], v[120:123]
	v_mfma_f32_16x16x32_bf16 v[108:111], v[130:133], v[170:173], v[108:111]
	v_mfma_f32_16x16x32_bf16 v[104:107], v[138:141], v[170:173], v[104:107]
	v_mfma_f32_16x16x32_bf16 v[92:95], v[130:133], v[178:181], v[92:95]
	v_mfma_f32_16x16x32_bf16 v[88:91], v[138:141], v[178:181], v[88:91]
	v_mfma_f32_16x16x32_bf16 v[76:79], v[130:133], v[200:203], v[76:79]
	v_mfma_f32_16x16x32_bf16 v[72:75], v[138:141], v[200:203], v[72:75]
	v_mfma_f32_16x16x32_bf16 v[124:127], v[134:137], v[166:169], v[124:127]
	v_mfma_f32_16x16x32_bf16 v[120:123], v[142:145], v[166:169], v[120:123]
	v_mfma_f32_16x16x32_bf16 v[108:111], v[134:137], v[174:177], v[108:111]
	v_mfma_f32_16x16x32_bf16 v[104:107], v[142:145], v[174:177], v[104:107]
	v_mfma_f32_16x16x32_bf16 v[92:95], v[134:137], v[196:199], v[92:95]
	v_mfma_f32_16x16x32_bf16 v[88:91], v[142:145], v[196:199], v[88:91]
	v_mfma_f32_16x16x32_bf16 v[76:79], v[134:137], v[204:207], v[76:79]
	v_mfma_f32_16x16x32_bf16 v[72:75], v[142:145], v[204:207], v[72:75]
	s_setprio 0
	s_setprio 1
	v_mfma_f32_16x16x32_bf16 v[116:119], v[146:149], v[162:165], v[116:119]
	v_mfma_f32_16x16x32_bf16 v[112:115], v[154:157], v[162:165], v[112:115]
	v_mfma_f32_16x16x32_bf16 v[100:103], v[146:149], v[170:173], v[100:103]
	v_mfma_f32_16x16x32_bf16 v[96:99], v[154:157], v[170:173], v[96:99]
	v_mfma_f32_16x16x32_bf16 v[84:87], v[146:149], v[178:181], v[84:87]
	v_mfma_f32_16x16x32_bf16 v[80:83], v[154:157], v[178:181], v[80:83]
	v_mfma_f32_16x16x32_bf16 v[68:71], v[146:149], v[200:203], v[68:71]
	v_mfma_f32_16x16x32_bf16 v[64:67], v[154:157], v[200:203], v[64:67]
	v_mfma_f32_16x16x32_bf16 v[116:119], v[150:153], v[166:169], v[116:119]
	v_mfma_f32_16x16x32_bf16 v[112:115], v[158:161], v[166:169], v[112:115]
	v_mfma_f32_16x16x32_bf16 v[100:103], v[150:153], v[174:177], v[100:103]
	v_mfma_f32_16x16x32_bf16 v[96:99], v[158:161], v[174:177], v[96:99]
	v_mfma_f32_16x16x32_bf16 v[84:87], v[150:153], v[196:199], v[84:87]
	v_mfma_f32_16x16x32_bf16 v[80:83], v[158:161], v[196:199], v[80:83]
	v_mfma_f32_16x16x32_bf16 v[68:71], v[150:153], v[204:207], v[68:71]
	v_mfma_f32_16x16x32_bf16 v[64:67], v[158:161], v[204:207], v[64:67]
	s_setprio 0
	s_barrier
	s_add_i32 s30, s30, s33
	s_mov_b32 m0, s30
	s_add_i32 s31, s30, 0x2000
	ds_read_b128 v[162:165], v191 offset:49152
	ds_read_b128 v[166:169], v191 offset:50176
	ds_read_b128 v[170:173], v191 offset:51200
	ds_read_b128 v[174:177], v191 offset:52224
	ds_read_b128 v[178:181], v191 offset:53248
	ds_read_b128 v[196:199], v191 offset:54272
	ds_read_b128 v[200:203], v191 offset:55296
	ds_read_b128 v[204:207], v191 offset:56320
	global_load_lds_dwordx4 v186, s[28:29]
	s_mov_b32 m0, s31
	s_add_i32 s56, s56, s33
	global_load_lds_dwordx4 v190, s[28:29]
	s_mov_b32 m0, s56
	s_add_i32 s57, s56, 0x2000
	global_load_lds_dwordx4 v186, s[6:7]
	s_mov_b32 m0, s57
	s_nop 0
	global_load_lds_dwordx4 v190, s[6:7]
	s_mov_b32 m0, s39
	s_nop 0
	global_load_lds_dwordx4 v184, s[26:27]
	s_mov_b32 m0, s40
	s_nop 0
	global_load_lds_dwordx4 v188, s[26:27]
	s_waitcnt vmcnt(8)
	s_waitcnt lgkmcnt(0)
	s_barrier
	s_setprio 1
	s_waitcnt lgkmcnt(0)
	v_mfma_f32_16x16x32_bf16 v[60:63], v[130:133], v[162:165], v[60:63]
	v_mfma_f32_16x16x32_bf16 v[56:59], v[138:141], v[162:165], v[56:59]
	v_mfma_f32_16x16x32_bf16 v[44:47], v[130:133], v[170:173], v[44:47]
	v_mfma_f32_16x16x32_bf16 v[40:43], v[138:141], v[170:173], v[40:43]
	v_mfma_f32_16x16x32_bf16 v[28:31], v[130:133], v[178:181], v[28:31]
	v_mfma_f32_16x16x32_bf16 v[24:27], v[138:141], v[178:181], v[24:27]
	v_mfma_f32_16x16x32_bf16 v[12:15], v[130:133], v[200:203], v[12:15]
	v_mfma_f32_16x16x32_bf16 v[8:11], v[138:141], v[200:203], v[8:11]
	v_mfma_f32_16x16x32_bf16 v[60:63], v[134:137], v[166:169], v[60:63]
	v_mfma_f32_16x16x32_bf16 v[56:59], v[142:145], v[166:169], v[56:59]
	v_mfma_f32_16x16x32_bf16 v[44:47], v[134:137], v[174:177], v[44:47]
	v_mfma_f32_16x16x32_bf16 v[40:43], v[142:145], v[174:177], v[40:43]
	v_mfma_f32_16x16x32_bf16 v[28:31], v[134:137], v[196:199], v[28:31]
	v_mfma_f32_16x16x32_bf16 v[24:27], v[142:145], v[196:199], v[24:27]
	v_mfma_f32_16x16x32_bf16 v[12:15], v[134:137], v[204:207], v[12:15]
	v_mfma_f32_16x16x32_bf16 v[8:11], v[142:145], v[204:207], v[8:11]
	s_setprio 0
	s_setprio 1
	v_mfma_f32_16x16x32_bf16 v[52:55], v[146:149], v[162:165], v[52:55]
	v_mfma_f32_16x16x32_bf16 v[48:51], v[154:157], v[162:165], v[48:51]
	v_mfma_f32_16x16x32_bf16 v[36:39], v[146:149], v[170:173], v[36:39]
	v_mfma_f32_16x16x32_bf16 v[32:35], v[154:157], v[170:173], v[32:35]
	v_mfma_f32_16x16x32_bf16 v[20:23], v[146:149], v[178:181], v[20:23]
	v_mfma_f32_16x16x32_bf16 v[16:19], v[154:157], v[178:181], v[16:19]
	v_mfma_f32_16x16x32_bf16 v[4:7], v[146:149], v[200:203], v[4:7]
	v_mfma_f32_16x16x32_bf16 v[0:3], v[154:157], v[200:203], v[0:3]
	v_mfma_f32_16x16x32_bf16 v[52:55], v[150:153], v[166:169], v[52:55]
	v_mfma_f32_16x16x32_bf16 v[48:51], v[158:161], v[166:169], v[48:51]
	v_mfma_f32_16x16x32_bf16 v[36:39], v[150:153], v[174:177], v[36:39]
	v_mfma_f32_16x16x32_bf16 v[32:35], v[158:161], v[174:177], v[32:35]
	v_mfma_f32_16x16x32_bf16 v[20:23], v[150:153], v[196:199], v[20:23]
	v_mfma_f32_16x16x32_bf16 v[16:19], v[158:161], v[196:199], v[16:19]
	v_mfma_f32_16x16x32_bf16 v[4:7], v[150:153], v[204:207], v[4:7]
	v_mfma_f32_16x16x32_bf16 v[0:3], v[158:161], v[204:207], v[0:3]
	s_setprio 0
	s_barrier
	s_add_i32 s55, s55, 2
	s_cmp_lt_u32 s55, 14
	s_mov_b64 s[6:7], s[24:25]
	s_mov_b64 s[20:21], s[22:23]
